# hoisted rowss loads in FFN2 gate/up epilogue (P8 only) on deterministic base
# speedup vs baseline: 1.0020x; 1.0020x over previous
; __device__ __forceinline__ unsigned cvt_pk_bf16(float lo, float hi) { unsigned r; asm volatile("v_cvt_pk_bf16_f32 %0, %1, %2" : "=v"(r) : "v"(lo), "v"(hi)); return r; }
; __device__ __forceinline__ float silu_f(float g) { return g * __builtin_amdgcn_rcpf(1.0f + __builtin_amdgcn_exp2f(-1.44269504089f * g)); }
;     __device__ __forceinline__ void operator()(const f32x4 (&acc)[2][2][4][2], const Unit& u, int wr, int wc, int fr, int fq) const {
;     ...
;             for (int m = 0; m < 4; ++m) { bf16_t* rowp = O + (size_t)(row0 + ai * HALF + m * 16) * ldc + col0;
;                 const float rs = rowss ? 1.0f / sqrtf(rowss[row0 + ai * HALF + m * 16] * (1.0f / 2048.0f) + 1e-6f) : 1.0f;
;                 const f32x4 g0 = acc[ai][0][m][0] * rs, g1 = acc[ai][0][m][1] * rs, u0 = acc[ai][1][m][0] * rs, u1 = acc[ai][1][m][1] * rs;
;                 float h[8];
; #pragma unroll
;                 for (int j = 0; j < 4; ++j) { h[j] = silu_f(g0[j]) * u0[j]; h[4 + j] = silu_f(g1[j]) * u1[j]; }
;                 u32x4 w; w.x = cvt_pk_bf16(h[0], h[1]); w.y = cvt_pk_bf16(h[2], h[3]); w.z = cvt_pk_bf16(h[4], h[5]); w.w = cvt_pk_bf16(h[6], h[7]);
;                 *(u32x4*)rowp = w; }
.LBB0_932:
	v_lshl_add_u32 v144, s4, 8, v150
	v_ashrrev_i32_e32 v145, 31, v144
	v_lshl_add_u64 v[148:149], v[144:145], 2, s[10:11]
	global_load_dword v145, v[148:149], off
	global_load_dword v199, v[148:149], off offset:64
	global_load_dword v200, v[148:149], off offset:128
	global_load_dword v201, v[148:149], off offset:192
	global_load_dword v202, v[148:149], off offset:512
	global_load_dword v203, v[148:149], off offset:576
	global_load_dword v204, v[148:149], off offset:640
	global_load_dword v205, v[148:149], off offset:704
	v_mov_b32_e32 v162, v120
	v_mov_b32_e32 v163, v112
	v_mov_b32_e32 v112, v121
	v_lshl_or_b32 v158, s5, 7, v152
	v_ashrrev_i32_e32 v159, 31, v158
	v_mov_b64_e32 v[146:147], s[74:75]
	v_mov_b32_e32 v164, v122
	v_mov_b32_e32 v165, v114
	v_mov_b32_e32 v114, v123
	v_mad_i64_i32 v[122:123], s[4:5], v144, s43, v[146:147]
	v_mov_b32_e32 v160, v124
	v_mov_b32_e32 v124, v126
	v_or_b32_e32 v126, 16, v144
	v_mov_b32_e32 v161, v116
	v_mov_b32_e32 v116, v125
	v_mov_b32_e32 v125, v118
	v_mov_b32_e32 v118, v127
	v_ashrrev_i32_e32 v127, 31, v126
	s_waitcnt vmcnt(7)
	v_fmamk_f32 v120, v145, 0x3a000000, v156
	s_nop 1
	v_rsq_f32_e32 v145, v120
	v_lshlrev_b64 v[120:121], 1, v[158:159]
	v_lshl_add_u64 v[122:123], v[122:123], 0, v[120:121]
	s_nop 1
	s_nop 0
	v_mov_b32_e32 v145, v145
	v_lshl_add_u64 v[158:159], v[126:127], 2, s[10:11]
	s_nop 0
	v_mov_b32_e32 v166, v145
	v_pk_mul_f32 v[116:117], v[116:117], v[166:167] op_sel_hi:[1,0]
	v_pk_mul_f32 v[112:113], v[112:113], v[166:167] op_sel_hi:[1,0]
	v_pk_mul_f32 v[124:125], v[124:125], v[166:167] op_sel_hi:[1,0]
	v_pk_mul_f32 v[114:115], v[114:115], v[166:167] op_sel_hi:[1,0]
	v_pk_mul_f32 v[160:161], v[160:161], v[166:167] op_sel_hi:[1,0]
	v_pk_mul_f32 v[162:163], v[162:163], v[166:167] op_sel_hi:[1,0]
	v_pk_mul_f32 v[164:165], v[164:165], v[166:167] op_sel_hi:[1,0]
	v_pk_mul_f32 v[118:119], v[118:119], v[166:167] op_sel_hi:[1,0]
	v_mul_f32_e32 v166, 0xbfb8aa3b, v117
	v_mul_f32_e32 v167, 0xbfb8aa3b, v113
	v_mul_f32_e32 v168, 0xbfb8aa3b, v125
	v_mul_f32_e32 v171, 0xbfb8aa3b, v115
	v_mul_f32_e32 v127, 0xbfb8aa3b, v161
	v_mul_f32_e32 v145, 0xbfb8aa3b, v163
	v_mul_f32_e32 v169, 0xbfb8aa3b, v165
	v_mul_f32_e32 v170, 0xbfb8aa3b, v119
	v_exp_f32_e32 v166, v166
	v_exp_f32_e32 v167, v167
	v_exp_f32_e32 v168, v168
	v_exp_f32_e32 v171, v171
	v_exp_f32_e32 v127, v127
	v_exp_f32_e32 v145, v145
	v_exp_f32_e32 v169, v169
	v_exp_f32_e32 v170, v170
	v_add_f32_e32 v166, 1.0, v166
	v_add_f32_e32 v167, 1.0, v167
	v_add_f32_e32 v168, 1.0, v168
	v_add_f32_e32 v171, 1.0, v171
	v_add_f32_e32 v127, 1.0, v127
	v_add_f32_e32 v145, 1.0, v145
	v_add_f32_e32 v169, 1.0, v169
	v_add_f32_e32 v170, 1.0, v170
	v_rcp_f32_e32 v166, v166
	v_rcp_f32_e32 v167, v167
	v_rcp_f32_e32 v168, v168
	v_rcp_f32_e32 v171, v171
	v_rcp_f32_e32 v127, v127
	v_rcp_f32_e32 v145, v145
	v_rcp_f32_e32 v169, v169
	v_rcp_f32_e32 v170, v170
	v_mul_f32_e32 v117, v117, v166
	v_mul_f32_e32 v113, v113, v167
	v_mul_f32_e32 v125, v125, v168
	v_mul_f32_e32 v115, v115, v171
	v_mul_f32_e32 v127, v161, v127
	v_mul_f32_e32 v145, v163, v145
	v_mul_f32_e32 v161, v165, v169
	v_mul_f32_e32 v119, v119, v170
	v_mul_f32_e32 v116, v116, v117
	v_mul_f32_e32 v117, v112, v113
	v_mul_f32_e32 v113, v124, v125
	v_mul_f32_e32 v115, v114, v115
	v_mul_f32_e32 v127, v160, v127
	v_mul_f32_e32 v145, v162, v145
	v_mul_f32_e32 v124, v164, v161
	v_mul_f32_e32 v118, v118, v119
	v_cvt_pk_bf16_f32 v112, v127, v116
	v_cvt_pk_bf16_f32 v113, v113, v118
	v_cvt_pk_bf16_f32 v114, v145, v117
	v_cvt_pk_bf16_f32 v115, v124, v115
	global_store_dwordx4 v[122:123], v[112:115], off
	s_waitcnt vmcnt(7)
	v_mov_b32_e32 v116, v199
	s_nop 0
	v_mov_b32_e32 v113, v100
	v_mov_b32_e32 v100, v109
	v_mov_b32_e32 v109, v98
	v_mov_b32_e32 v98, v107
	v_mov_b32_e32 v114, v104
	v_mov_b32_e32 v104, v110
	v_mov_b32_e32 v115, v96
	v_mov_b32_e32 v96, v105
	v_mov_b32_e32 v105, v102
	v_mov_b32_e32 v102, v111
	v_mov_b32_e32 v112, v108
	v_mov_b32_e32 v108, v106
	v_or_b32_e32 v106, 32, v144
	v_fmamk_f32 v107, v116, 0x3a000000, v156
	s_nop 1
	v_rsq_f32_e32 v116, v107
	v_mad_i64_i32 v[110:111], s[4:5], v126, s43, v[146:147]
	v_ashrrev_i32_e32 v107, 31, v106
	v_lshl_add_u64 v[110:111], v[110:111], 0, v[120:121]
	s_nop 0
	s_nop 1
	s_nop 0
	v_mov_b32_e32 v118, v116
	v_lshl_add_u64 v[116:117], v[106:107], 2, s[10:11]
	s_nop 0
	v_mov_b32_e32 v118, v118
	v_pk_mul_f32 v[100:101], v[100:101], v[118:119] op_sel_hi:[1,0]
	v_pk_mul_f32 v[96:97], v[96:97], v[118:119] op_sel_hi:[1,0]
	v_pk_mul_f32 v[104:105], v[104:105], v[118:119] op_sel_hi:[1,0]
	v_pk_mul_f32 v[98:99], v[98:99], v[118:119] op_sel_hi:[1,0]
	v_pk_mul_f32 v[112:113], v[112:113], v[118:119] op_sel_hi:[1,0]
	v_pk_mul_f32 v[114:115], v[114:115], v[118:119] op_sel_hi:[1,0]
	v_pk_mul_f32 v[108:109], v[108:109], v[118:119] op_sel_hi:[1,0]
	v_pk_mul_f32 v[102:103], v[102:103], v[118:119] op_sel_hi:[1,0]
	v_mul_f32_e32 v119, 0xbfb8aa3b, v101
	v_mul_f32_e32 v122, 0xbfb8aa3b, v97
	v_mul_f32_e32 v123, 0xbfb8aa3b, v105
	v_mul_f32_e32 v126, 0xbfb8aa3b, v99
	v_mul_f32_e32 v107, 0xbfb8aa3b, v113
	v_mul_f32_e32 v118, 0xbfb8aa3b, v115
	v_mul_f32_e32 v124, 0xbfb8aa3b, v109
	v_mul_f32_e32 v125, 0xbfb8aa3b, v103
	v_exp_f32_e32 v119, v119
	v_exp_f32_e32 v122, v122
	v_exp_f32_e32 v123, v123
	v_exp_f32_e32 v126, v126
	v_exp_f32_e32 v107, v107
	v_exp_f32_e32 v118, v118
	v_exp_f32_e32 v124, v124
	v_exp_f32_e32 v125, v125
	v_add_f32_e32 v119, 1.0, v119
	v_add_f32_e32 v122, 1.0, v122
	v_add_f32_e32 v123, 1.0, v123
	v_add_f32_e32 v126, 1.0, v126
	v_add_f32_e32 v107, 1.0, v107
	v_add_f32_e32 v118, 1.0, v118
	v_add_f32_e32 v124, 1.0, v124
	v_add_f32_e32 v125, 1.0, v125
	v_rcp_f32_e32 v119, v119
	v_rcp_f32_e32 v122, v122
	v_rcp_f32_e32 v123, v123
	v_rcp_f32_e32 v126, v126
	v_rcp_f32_e32 v107, v107
	v_rcp_f32_e32 v118, v118
	v_rcp_f32_e32 v124, v124
	v_rcp_f32_e32 v125, v125
	v_mul_f32_e32 v101, v101, v119
	v_mul_f32_e32 v97, v97, v122
	v_mul_f32_e32 v105, v105, v123
	v_mul_f32_e32 v99, v99, v126
	v_mul_f32_e32 v107, v113, v107
	v_mul_f32_e32 v113, v115, v118
	v_mul_f32_e32 v109, v109, v124
	v_mul_f32_e32 v103, v103, v125
	v_mul_f32_e32 v100, v100, v101
	v_mul_f32_e32 v101, v96, v97
	v_mul_f32_e32 v97, v104, v105
	v_mul_f32_e32 v99, v98, v99
	v_mul_f32_e32 v107, v112, v107
	v_mul_f32_e32 v112, v114, v113
	v_mul_f32_e32 v104, v108, v109
	v_mul_f32_e32 v102, v102, v103
	v_cvt_pk_bf16_f32 v96, v107, v100
	v_cvt_pk_bf16_f32 v97, v97, v102
	v_cvt_pk_bf16_f32 v98, v112, v101
	v_cvt_pk_bf16_f32 v99, v104, v99
	global_store_dwordx4 v[110:111], v[96:99], off
	s_waitcnt vmcnt(7)
; __device__ __forceinline__ unsigned cvt_pk_bf16(float lo, float hi) { unsigned r; asm volatile("v_cvt_pk_bf16_f32 %0, %1, %2" : "=v"(r) : "v"(lo), "v"(hi)); return r; }
; __device__ __forceinline__ float silu_f(float g) { return g * __builtin_amdgcn_rcpf(1.0f + __builtin_amdgcn_exp2f(-1.44269504089f * g)); }
;     __device__ __forceinline__ void operator()(const f32x4 (&acc)[2][2][4][2], const Unit& u, int wr, int wc, int fr, int fq) const {
;     ...
;             for (int m = 0; m < 4; ++m) { bf16_t* rowp = O + (size_t)(row0 + ai * HALF + m * 16) * ldc + col0;
;                 const float rs = rowss ? 1.0f / sqrtf(rowss[row0 + ai * HALF + m * 16] * (1.0f / 2048.0f) + 1e-6f) : 1.0f;
;                 const f32x4 g0 = acc[ai][0][m][0] * rs, g1 = acc[ai][0][m][1] * rs, u0 = acc[ai][1][m][0] * rs, u1 = acc[ai][1][m][1] * rs;
;                 float h[8];
; #pragma unroll
;                 for (int j = 0; j < 4; ++j) { h[j] = silu_f(g0[j]) * u0[j]; h[4 + j] = silu_f(g1[j]) * u1[j]; }
;                 u32x4 w; w.x = cvt_pk_bf16(h[0], h[1]); w.y = cvt_pk_bf16(h[2], h[3]); w.z = cvt_pk_bf16(h[4], h[5]); w.w = cvt_pk_bf16(h[6], h[7]);
;                 *(u32x4*)rowp = w; }
	v_mov_b32_e32 v100, v200
	s_nop 0
	v_mov_b32_e32 v97, v84
	v_mov_b32_e32 v84, v93
	v_mov_b32_e32 v93, v82
	v_mov_b32_e32 v82, v91
	v_mov_b32_e32 v98, v88
	v_mov_b32_e32 v88, v94
	v_mov_b32_e32 v99, v80
	v_mov_b32_e32 v80, v89
	v_mov_b32_e32 v89, v86
	v_mov_b32_e32 v86, v95
	v_mov_b32_e32 v96, v92
	v_mov_b32_e32 v92, v90
	v_or_b32_e32 v90, 48, v144
	v_fmamk_f32 v91, v100, 0x3a000000, v156
	s_nop 1
	v_rsq_f32_e32 v100, v91
	v_mad_i64_i32 v[94:95], s[4:5], v106, s43, v[146:147]
	v_ashrrev_i32_e32 v91, 31, v90
	v_lshl_add_u64 v[94:95], v[94:95], 0, v[120:121]
	s_nop 0
	s_nop 1
	s_nop 0
	v_mov_b32_e32 v102, v100
	v_lshl_add_u64 v[100:101], v[90:91], 2, s[10:11]
	s_nop 0
	v_mov_b32_e32 v102, v102
	v_pk_mul_f32 v[84:85], v[84:85], v[102:103] op_sel_hi:[1,0]
	v_pk_mul_f32 v[80:81], v[80:81], v[102:103] op_sel_hi:[1,0]
	v_pk_mul_f32 v[88:89], v[88:89], v[102:103] op_sel_hi:[1,0]
	v_pk_mul_f32 v[82:83], v[82:83], v[102:103] op_sel_hi:[1,0]
	v_pk_mul_f32 v[96:97], v[96:97], v[102:103] op_sel_hi:[1,0]
	v_pk_mul_f32 v[98:99], v[98:99], v[102:103] op_sel_hi:[1,0]
	v_pk_mul_f32 v[92:93], v[92:93], v[102:103] op_sel_hi:[1,0]
	v_pk_mul_f32 v[86:87], v[86:87], v[102:103] op_sel_hi:[1,0]
	v_mul_f32_e32 v103, 0xbfb8aa3b, v85
	v_mul_f32_e32 v104, 0xbfb8aa3b, v81
	v_mul_f32_e32 v105, 0xbfb8aa3b, v89
	v_mul_f32_e32 v108, 0xbfb8aa3b, v83
	v_mul_f32_e32 v91, 0xbfb8aa3b, v97
	v_mul_f32_e32 v102, 0xbfb8aa3b, v99
	v_mul_f32_e32 v106, 0xbfb8aa3b, v93
	v_mul_f32_e32 v107, 0xbfb8aa3b, v87
	v_exp_f32_e32 v103, v103
	v_exp_f32_e32 v104, v104
	v_exp_f32_e32 v105, v105
	v_exp_f32_e32 v108, v108
	v_exp_f32_e32 v91, v91
	v_exp_f32_e32 v102, v102
	v_exp_f32_e32 v106, v106
	v_exp_f32_e32 v107, v107
	v_add_f32_e32 v103, 1.0, v103
	v_add_f32_e32 v104, 1.0, v104
	v_add_f32_e32 v105, 1.0, v105
	v_add_f32_e32 v108, 1.0, v108
	v_add_f32_e32 v91, 1.0, v91
	v_add_f32_e32 v102, 1.0, v102
	v_add_f32_e32 v106, 1.0, v106
	v_add_f32_e32 v107, 1.0, v107
	v_rcp_f32_e32 v103, v103
	v_rcp_f32_e32 v104, v104
	v_rcp_f32_e32 v105, v105
	v_rcp_f32_e32 v108, v108
	v_rcp_f32_e32 v91, v91
	v_rcp_f32_e32 v102, v102
	v_rcp_f32_e32 v106, v106
	v_rcp_f32_e32 v107, v107
	v_mul_f32_e32 v85, v85, v103
	v_mul_f32_e32 v81, v81, v104
	v_mul_f32_e32 v89, v89, v105
	v_mul_f32_e32 v83, v83, v108
	v_mul_f32_e32 v91, v97, v91
	v_mul_f32_e32 v97, v99, v102
	v_mul_f32_e32 v93, v93, v106
	v_mul_f32_e32 v87, v87, v107
	v_mul_f32_e32 v84, v84, v85
	v_mul_f32_e32 v85, v80, v81
	v_mul_f32_e32 v81, v88, v89
	v_mul_f32_e32 v83, v82, v83
	v_mul_f32_e32 v91, v96, v91
	v_mul_f32_e32 v96, v98, v97
	v_mul_f32_e32 v88, v92, v93
	v_mul_f32_e32 v86, v86, v87
	v_cvt_pk_bf16_f32 v80, v91, v84
	v_cvt_pk_bf16_f32 v81, v81, v86
	v_cvt_pk_bf16_f32 v82, v96, v85
	v_cvt_pk_bf16_f32 v83, v88, v83
	global_store_dwordx4 v[94:95], v[80:83], off
	s_waitcnt vmcnt(7)
	v_mov_b32_e32 v84, v201
	s_nop 0
	v_mov_b32_e32 v81, v72
	v_mov_b32_e32 v72, v77
	v_mov_b32_e32 v77, v66
	v_mov_b32_e32 v80, v76
	v_mov_b32_e32 v76, v70
	v_mov_b32_e32 v82, v68
	v_mov_b32_e32 v68, v78
	v_mov_b32_e32 v83, v64
	v_mov_b32_e32 v64, v69
	v_mov_b32_e32 v69, v74
	v_mov_b32_e32 v74, v79
	v_fmamk_f32 v66, v84, 0x3a000000, v156
	s_nop 1
	v_rsq_f32_e32 v78, v66
	v_mov_b32_e32 v66, v71
	v_mad_i64_i32 v[70:71], s[4:5], v90, s43, v[146:147]
	v_lshl_add_u64 v[70:71], v[70:71], 0, v[120:121]
	s_nop 0
	s_nop 1
	s_nop 0
	v_mov_b32_e32 v78, v78
	s_nop 0
	v_mov_b32_e32 v78, v78
	v_pk_mul_f32 v[72:73], v[72:73], v[78:79] op_sel_hi:[1,0]
	v_pk_mul_f32 v[64:65], v[64:65], v[78:79] op_sel_hi:[1,0]
	v_pk_mul_f32 v[68:69], v[68:69], v[78:79] op_sel_hi:[1,0]
	v_pk_mul_f32 v[66:67], v[66:67], v[78:79] op_sel_hi:[1,0]
	v_pk_mul_f32 v[80:81], v[80:81], v[78:79] op_sel_hi:[1,0]
	v_pk_mul_f32 v[82:83], v[82:83], v[78:79] op_sel_hi:[1,0]
	v_pk_mul_f32 v[76:77], v[76:77], v[78:79] op_sel_hi:[1,0]
	v_pk_mul_f32 v[74:75], v[74:75], v[78:79] op_sel_hi:[1,0]
	v_mul_f32_e32 v84, 0xbfb8aa3b, v73
	v_mul_f32_e32 v85, 0xbfb8aa3b, v65
	v_mul_f32_e32 v86, 0xbfb8aa3b, v69
	v_mul_f32_e32 v89, 0xbfb8aa3b, v67
	v_mul_f32_e32 v78, 0xbfb8aa3b, v81
	v_mul_f32_e32 v79, 0xbfb8aa3b, v83
	v_mul_f32_e32 v87, 0xbfb8aa3b, v77
	v_mul_f32_e32 v88, 0xbfb8aa3b, v75
	v_exp_f32_e32 v84, v84
	v_exp_f32_e32 v85, v85
	v_exp_f32_e32 v86, v86
	v_exp_f32_e32 v89, v89
	v_exp_f32_e32 v78, v78
	v_exp_f32_e32 v79, v79
	v_exp_f32_e32 v87, v87
	v_exp_f32_e32 v88, v88
	v_add_f32_e32 v84, 1.0, v84
	v_add_f32_e32 v85, 1.0, v85
	v_add_f32_e32 v86, 1.0, v86
	v_add_f32_e32 v89, 1.0, v89
	v_add_f32_e32 v78, 1.0, v78
	v_add_f32_e32 v79, 1.0, v79
	v_add_f32_e32 v87, 1.0, v87
	v_add_f32_e32 v88, 1.0, v88
	v_rcp_f32_e32 v84, v84
	v_rcp_f32_e32 v85, v85
	v_rcp_f32_e32 v86, v86
	v_rcp_f32_e32 v89, v89
	v_rcp_f32_e32 v78, v78
	v_rcp_f32_e32 v79, v79
	v_rcp_f32_e32 v87, v87
	v_rcp_f32_e32 v88, v88
	v_mul_f32_e32 v73, v73, v84
	v_mul_f32_e32 v65, v65, v85
	v_mul_f32_e32 v69, v69, v86
	v_mul_f32_e32 v67, v67, v89
	v_mul_f32_e32 v78, v81, v78
	v_mul_f32_e32 v79, v83, v79
	v_mul_f32_e32 v77, v77, v87
	v_mul_f32_e32 v75, v75, v88
	v_mul_f32_e32 v72, v72, v73
	v_mul_f32_e32 v73, v64, v65
	v_mul_f32_e32 v65, v68, v69
	v_mul_f32_e32 v67, v66, v67
	v_mul_f32_e32 v78, v80, v78
	v_mul_f32_e32 v79, v82, v79
	v_mul_f32_e32 v68, v76, v77
	v_mul_f32_e32 v69, v74, v75
	v_cvt_pk_bf16_f32 v64, v78, v72
	v_cvt_pk_bf16_f32 v65, v65, v69
	v_cvt_pk_bf16_f32 v66, v79, v73
	v_cvt_pk_bf16_f32 v67, v68, v67
	global_store_dwordx4 v[70:71], v[64:67], off
	s_waitcnt vmcnt(7)
; __device__ __forceinline__ unsigned cvt_pk_bf16(float lo, float hi) { unsigned r; asm volatile("v_cvt_pk_bf16_f32 %0, %1, %2" : "=v"(r) : "v"(lo), "v"(hi)); return r; }
; __device__ __forceinline__ float silu_f(float g) { return g * __builtin_amdgcn_rcpf(1.0f + __builtin_amdgcn_exp2f(-1.44269504089f * g)); }
;     __device__ __forceinline__ void operator()(const f32x4 (&acc)[2][2][4][2], const Unit& u, int wr, int wc, int fr, int fq) const {
;     ...
;             for (int m = 0; m < 4; ++m) { bf16_t* rowp = O + (size_t)(row0 + ai * HALF + m * 16) * ldc + col0;
;                 const float rs = rowss ? 1.0f / sqrtf(rowss[row0 + ai * HALF + m * 16] * (1.0f / 2048.0f) + 1e-6f) : 1.0f;
;                 const f32x4 g0 = acc[ai][0][m][0] * rs, g1 = acc[ai][0][m][1] * rs, u0 = acc[ai][1][m][0] * rs, u1 = acc[ai][1][m][1] * rs;
;                 float h[8];
; #pragma unroll
;                 for (int j = 0; j < 4; ++j) { h[j] = silu_f(g0[j]) * u0[j]; h[4 + j] = silu_f(g1[j]) * u1[j]; }
;                 u32x4 w; w.x = cvt_pk_bf16(h[0], h[1]); w.y = cvt_pk_bf16(h[2], h[3]); w.z = cvt_pk_bf16(h[4], h[5]); w.w = cvt_pk_bf16(h[6], h[7]);
;                 *(u32x4*)rowp = w; }
	v_mov_b32_e32 v68, v202
	s_nop 0
	v_mov_b32_e32 v64, v60
	v_mov_b32_e32 v60, v58
	v_mov_b32_e32 v65, v52
	v_mov_b32_e32 v52, v61
	v_mov_b32_e32 v61, v50
	v_mov_b32_e32 v50, v59
	v_mov_b32_e32 v66, v56
	v_mov_b32_e32 v56, v62
	v_mov_b32_e32 v67, v48
	v_mov_b32_e32 v48, v57
	v_mov_b32_e32 v57, v54
	v_mov_b32_e32 v54, v63
	v_fmamk_f32 v58, v68, 0x3a000000, v156
	s_nop 1
	v_rsq_f32_e32 v62, v58
	v_add_u32_e32 v58, 0x80, v144
	v_mad_i64_i32 v[58:59], s[4:5], v58, s43, v[146:147]
	v_lshl_add_u64 v[58:59], v[58:59], 0, v[120:121]
	s_nop 0
	s_nop 1
	s_nop 0
	v_mov_b32_e32 v62, v62
	s_nop 0
	v_mov_b32_e32 v62, v62
	v_pk_mul_f32 v[52:53], v[52:53], v[62:63] op_sel_hi:[1,0]
	v_pk_mul_f32 v[48:49], v[48:49], v[62:63] op_sel_hi:[1,0]
	v_pk_mul_f32 v[56:57], v[56:57], v[62:63] op_sel_hi:[1,0]
	v_pk_mul_f32 v[50:51], v[50:51], v[62:63] op_sel_hi:[1,0]
	v_pk_mul_f32 v[64:65], v[64:65], v[62:63] op_sel_hi:[1,0]
	v_pk_mul_f32 v[66:67], v[66:67], v[62:63] op_sel_hi:[1,0]
	v_pk_mul_f32 v[60:61], v[60:61], v[62:63] op_sel_hi:[1,0]
	v_pk_mul_f32 v[54:55], v[54:55], v[62:63] op_sel_hi:[1,0]
	v_mul_f32_e32 v68, 0xbfb8aa3b, v53
	v_mul_f32_e32 v69, 0xbfb8aa3b, v49
	v_mul_f32_e32 v70, 0xbfb8aa3b, v57
	v_mul_f32_e32 v73, 0xbfb8aa3b, v51
	v_mul_f32_e32 v62, 0xbfb8aa3b, v65
	v_mul_f32_e32 v63, 0xbfb8aa3b, v67
	v_mul_f32_e32 v71, 0xbfb8aa3b, v61
	v_mul_f32_e32 v72, 0xbfb8aa3b, v55
	v_exp_f32_e32 v68, v68
	v_exp_f32_e32 v69, v69
	v_exp_f32_e32 v70, v70
	v_exp_f32_e32 v73, v73
	v_exp_f32_e32 v62, v62
	v_exp_f32_e32 v63, v63
	v_exp_f32_e32 v71, v71
	v_exp_f32_e32 v72, v72
	v_add_f32_e32 v68, 1.0, v68
	v_add_f32_e32 v69, 1.0, v69
	v_add_f32_e32 v70, 1.0, v70
	v_add_f32_e32 v73, 1.0, v73
	v_add_f32_e32 v62, 1.0, v62
	v_add_f32_e32 v63, 1.0, v63
	v_add_f32_e32 v71, 1.0, v71
	v_add_f32_e32 v72, 1.0, v72
	v_rcp_f32_e32 v68, v68
	v_rcp_f32_e32 v69, v69
	v_rcp_f32_e32 v70, v70
	v_rcp_f32_e32 v73, v73
	v_rcp_f32_e32 v62, v62
	v_rcp_f32_e32 v63, v63
	v_rcp_f32_e32 v71, v71
	v_rcp_f32_e32 v72, v72
	v_mul_f32_e32 v53, v53, v68
	v_mul_f32_e32 v49, v49, v69
	v_mul_f32_e32 v57, v57, v70
	v_mul_f32_e32 v51, v51, v73
	v_mul_f32_e32 v62, v65, v62
	v_mul_f32_e32 v63, v67, v63
	v_mul_f32_e32 v61, v61, v71
	v_mul_f32_e32 v55, v55, v72
	v_mul_f32_e32 v52, v52, v53
	v_mul_f32_e32 v53, v48, v49
	v_mul_f32_e32 v49, v56, v57
	v_mul_f32_e32 v51, v50, v51
	v_mul_f32_e32 v62, v64, v62
	v_mul_f32_e32 v63, v66, v63
	v_mul_f32_e32 v56, v60, v61
	v_mul_f32_e32 v54, v54, v55
	v_cvt_pk_bf16_f32 v48, v62, v52
	v_cvt_pk_bf16_f32 v49, v49, v54
	v_cvt_pk_bf16_f32 v50, v63, v53
	v_cvt_pk_bf16_f32 v51, v56, v51
	global_store_dwordx4 v[58:59], v[48:51], off
	s_waitcnt vmcnt(7)
	v_mov_b32_e32 v52, v203
	s_nop 0
	v_mov_b32_e32 v48, v44
	v_mov_b32_e32 v44, v42
	v_mov_b32_e32 v49, v36
	v_mov_b32_e32 v36, v45
	v_mov_b32_e32 v45, v34
	v_mov_b32_e32 v34, v43
	v_mov_b32_e32 v50, v40
	v_mov_b32_e32 v40, v46
	v_mov_b32_e32 v51, v32
	v_mov_b32_e32 v32, v41
	v_mov_b32_e32 v41, v38
	v_mov_b32_e32 v38, v47
	v_fmamk_f32 v42, v52, 0x3a000000, v156
	s_nop 1
	v_rsq_f32_e32 v46, v42
	v_add_u32_e32 v42, 0x90, v144
	v_mad_i64_i32 v[42:43], s[4:5], v42, s43, v[146:147]
	v_lshl_add_u64 v[42:43], v[42:43], 0, v[120:121]
	s_nop 0
	s_nop 1
	s_nop 0
	v_mov_b32_e32 v46, v46
	s_nop 0
	v_mov_b32_e32 v46, v46
	v_pk_mul_f32 v[36:37], v[36:37], v[46:47] op_sel_hi:[1,0]
	v_pk_mul_f32 v[32:33], v[32:33], v[46:47] op_sel_hi:[1,0]
	v_pk_mul_f32 v[40:41], v[40:41], v[46:47] op_sel_hi:[1,0]
	v_pk_mul_f32 v[34:35], v[34:35], v[46:47] op_sel_hi:[1,0]
	v_pk_mul_f32 v[48:49], v[48:49], v[46:47] op_sel_hi:[1,0]
	v_pk_mul_f32 v[50:51], v[50:51], v[46:47] op_sel_hi:[1,0]
	v_pk_mul_f32 v[44:45], v[44:45], v[46:47] op_sel_hi:[1,0]
	v_pk_mul_f32 v[38:39], v[38:39], v[46:47] op_sel_hi:[1,0]
	v_mul_f32_e32 v52, 0xbfb8aa3b, v37
	v_mul_f32_e32 v53, 0xbfb8aa3b, v33
	v_mul_f32_e32 v54, 0xbfb8aa3b, v41
	v_mul_f32_e32 v57, 0xbfb8aa3b, v35
	v_mul_f32_e32 v46, 0xbfb8aa3b, v49
	v_mul_f32_e32 v47, 0xbfb8aa3b, v51
	v_mul_f32_e32 v55, 0xbfb8aa3b, v45
	v_mul_f32_e32 v56, 0xbfb8aa3b, v39
	v_exp_f32_e32 v52, v52
	v_exp_f32_e32 v53, v53
	v_exp_f32_e32 v54, v54
	v_exp_f32_e32 v57, v57
	v_exp_f32_e32 v46, v46
	v_exp_f32_e32 v47, v47
	v_exp_f32_e32 v55, v55
	v_exp_f32_e32 v56, v56
	v_add_f32_e32 v52, 1.0, v52
	v_add_f32_e32 v53, 1.0, v53
	v_add_f32_e32 v54, 1.0, v54
	v_add_f32_e32 v57, 1.0, v57
	v_add_f32_e32 v46, 1.0, v46
	v_add_f32_e32 v47, 1.0, v47
	v_add_f32_e32 v55, 1.0, v55
	v_add_f32_e32 v56, 1.0, v56
	v_rcp_f32_e32 v52, v52
	v_rcp_f32_e32 v53, v53
	v_rcp_f32_e32 v54, v54
	v_rcp_f32_e32 v57, v57
	v_rcp_f32_e32 v46, v46
	v_rcp_f32_e32 v47, v47
	v_rcp_f32_e32 v55, v55
	v_rcp_f32_e32 v56, v56
	v_mul_f32_e32 v37, v37, v52
	v_mul_f32_e32 v33, v33, v53
	v_mul_f32_e32 v41, v41, v54
	v_mul_f32_e32 v35, v35, v57
	v_mul_f32_e32 v46, v49, v46
	v_mul_f32_e32 v47, v51, v47
	v_mul_f32_e32 v45, v45, v55
	v_mul_f32_e32 v39, v39, v56
	v_mul_f32_e32 v36, v36, v37
	v_mul_f32_e32 v37, v32, v33
	v_mul_f32_e32 v33, v40, v41
	v_mul_f32_e32 v35, v34, v35
	v_mul_f32_e32 v46, v48, v46
	v_mul_f32_e32 v47, v50, v47
	v_mul_f32_e32 v40, v44, v45
	v_mul_f32_e32 v38, v38, v39
	v_cvt_pk_bf16_f32 v32, v46, v36
	v_cvt_pk_bf16_f32 v33, v33, v38
	v_cvt_pk_bf16_f32 v34, v47, v37
	v_cvt_pk_bf16_f32 v35, v40, v35
	global_store_dwordx4 v[42:43], v[32:35], off
	s_waitcnt vmcnt(7)
; __device__ __forceinline__ unsigned cvt_pk_bf16(float lo, float hi) { unsigned r; asm volatile("v_cvt_pk_bf16_f32 %0, %1, %2" : "=v"(r) : "v"(lo), "v"(hi)); return r; }
; __device__ __forceinline__ float silu_f(float g) { return g * __builtin_amdgcn_rcpf(1.0f + __builtin_amdgcn_exp2f(-1.44269504089f * g)); }
;     __device__ __forceinline__ void operator()(const f32x4 (&acc)[2][2][4][2], const Unit& u, int wr, int wc, int fr, int fq) const {
;     ...
;             for (int m = 0; m < 4; ++m) { bf16_t* rowp = O + (size_t)(row0 + ai * HALF + m * 16) * ldc + col0;
;                 const float rs = rowss ? 1.0f / sqrtf(rowss[row0 + ai * HALF + m * 16] * (1.0f / 2048.0f) + 1e-6f) : 1.0f;
;                 const f32x4 g0 = acc[ai][0][m][0] * rs, g1 = acc[ai][0][m][1] * rs, u0 = acc[ai][1][m][0] * rs, u1 = acc[ai][1][m][1] * rs;
;                 float h[8];
; #pragma unroll
;                 for (int j = 0; j < 4; ++j) { h[j] = silu_f(g0[j]) * u0[j]; h[4 + j] = silu_f(g1[j]) * u1[j]; }
;                 u32x4 w; w.x = cvt_pk_bf16(h[0], h[1]); w.y = cvt_pk_bf16(h[2], h[3]); w.z = cvt_pk_bf16(h[4], h[5]); w.w = cvt_pk_bf16(h[6], h[7]);
;                 *(u32x4*)rowp = w; }
	v_mov_b32_e32 v36, v204
	s_nop 0
	v_mov_b32_e32 v32, v28
	v_mov_b32_e32 v28, v26
	v_mov_b32_e32 v33, v20
	v_mov_b32_e32 v20, v29
	v_mov_b32_e32 v29, v18
	v_mov_b32_e32 v18, v27
	v_mov_b32_e32 v34, v24
	v_mov_b32_e32 v24, v30
	v_mov_b32_e32 v35, v16
	v_mov_b32_e32 v16, v25
	v_mov_b32_e32 v25, v22
	v_mov_b32_e32 v22, v31
	v_fmamk_f32 v26, v36, 0x3a000000, v156
	s_nop 1
	v_rsq_f32_e32 v30, v26
	v_add_u32_e32 v26, 0xa0, v144
	v_mad_i64_i32 v[26:27], s[4:5], v26, s43, v[146:147]
	v_lshl_add_u64 v[26:27], v[26:27], 0, v[120:121]
	s_nop 0
	s_nop 1
	s_nop 0
	v_mov_b32_e32 v30, v30
	s_nop 0
	v_mov_b32_e32 v30, v30
	v_pk_mul_f32 v[20:21], v[20:21], v[30:31] op_sel_hi:[1,0]
	v_pk_mul_f32 v[16:17], v[16:17], v[30:31] op_sel_hi:[1,0]
	v_pk_mul_f32 v[24:25], v[24:25], v[30:31] op_sel_hi:[1,0]
	v_pk_mul_f32 v[18:19], v[18:19], v[30:31] op_sel_hi:[1,0]
	v_pk_mul_f32 v[32:33], v[32:33], v[30:31] op_sel_hi:[1,0]
	v_pk_mul_f32 v[34:35], v[34:35], v[30:31] op_sel_hi:[1,0]
	v_pk_mul_f32 v[28:29], v[28:29], v[30:31] op_sel_hi:[1,0]
	v_pk_mul_f32 v[22:23], v[22:23], v[30:31] op_sel_hi:[1,0]
	v_mul_f32_e32 v36, 0xbfb8aa3b, v21
	v_mul_f32_e32 v37, 0xbfb8aa3b, v17
	v_mul_f32_e32 v38, 0xbfb8aa3b, v25
	v_mul_f32_e32 v41, 0xbfb8aa3b, v19
	v_mul_f32_e32 v30, 0xbfb8aa3b, v33
	v_mul_f32_e32 v31, 0xbfb8aa3b, v35
	v_mul_f32_e32 v39, 0xbfb8aa3b, v29
	v_mul_f32_e32 v40, 0xbfb8aa3b, v23
	v_exp_f32_e32 v36, v36
	v_exp_f32_e32 v37, v37
	v_exp_f32_e32 v38, v38
	v_exp_f32_e32 v41, v41
	v_exp_f32_e32 v30, v30
	v_exp_f32_e32 v31, v31
	v_exp_f32_e32 v39, v39
	v_exp_f32_e32 v40, v40
	v_add_f32_e32 v36, 1.0, v36
	v_add_f32_e32 v37, 1.0, v37
	v_add_f32_e32 v38, 1.0, v38
	v_add_f32_e32 v41, 1.0, v41
	v_add_f32_e32 v30, 1.0, v30
	v_add_f32_e32 v31, 1.0, v31
	v_add_f32_e32 v39, 1.0, v39
	v_add_f32_e32 v40, 1.0, v40
	v_rcp_f32_e32 v36, v36
	v_rcp_f32_e32 v37, v37
	v_rcp_f32_e32 v38, v38
	v_rcp_f32_e32 v41, v41
	v_rcp_f32_e32 v30, v30
	v_rcp_f32_e32 v31, v31
	v_rcp_f32_e32 v39, v39
	v_rcp_f32_e32 v40, v40
	v_mul_f32_e32 v21, v21, v36
	v_mul_f32_e32 v17, v17, v37
	v_mul_f32_e32 v25, v25, v38
	v_mul_f32_e32 v19, v19, v41
	v_mul_f32_e32 v30, v33, v30
	v_mul_f32_e32 v31, v35, v31
	v_mul_f32_e32 v29, v29, v39
	v_mul_f32_e32 v23, v23, v40
	v_mul_f32_e32 v20, v20, v21
	v_mul_f32_e32 v21, v16, v17
	v_mul_f32_e32 v17, v24, v25
	v_mul_f32_e32 v19, v18, v19
	v_mul_f32_e32 v30, v32, v30
	v_mul_f32_e32 v31, v34, v31
	v_mul_f32_e32 v24, v28, v29
	v_mul_f32_e32 v22, v22, v23
	v_cvt_pk_bf16_f32 v16, v30, v20
	v_cvt_pk_bf16_f32 v17, v17, v22
	v_cvt_pk_bf16_f32 v18, v31, v21
	v_cvt_pk_bf16_f32 v19, v24, v19
	global_store_dwordx4 v[26:27], v[16:19], off
	s_waitcnt vmcnt(7)
	v_mov_b32_e32 v20, v205
	s_nop 0
	v_mov_b32_e32 v17, v4
	v_mov_b32_e32 v4, v13
	v_mov_b32_e32 v13, v2
	v_mov_b32_e32 v2, v11
	v_mov_b32_e32 v18, v8
	v_mov_b32_e32 v8, v14
	v_mov_b32_e32 v19, v0
	v_mov_b32_e32 v0, v9
	v_mov_b32_e32 v9, v6
	v_mov_b32_e32 v6, v15
	v_mov_b32_e32 v16, v12
	v_mov_b32_e32 v12, v10
	v_add_u32_e32 v10, 0xb0, v144
	v_fmamk_f32 v11, v20, 0x3a000000, v156
	s_nop 1
	v_rsq_f32_e32 v14, v11
	v_mad_i64_i32 v[10:11], s[4:5], v10, s43, v[146:147]
	v_lshl_add_u64 v[10:11], v[10:11], 0, v[120:121]
	s_nop 1
	s_nop 0
	v_mov_b32_e32 v14, v14
	s_mov_b64 s[4:5], -1
	s_nop 0
	v_mov_b32_e32 v14, v14
	v_pk_mul_f32 v[4:5], v[4:5], v[14:15] op_sel_hi:[1,0]
	v_pk_mul_f32 v[0:1], v[0:1], v[14:15] op_sel_hi:[1,0]
	v_pk_mul_f32 v[8:9], v[8:9], v[14:15] op_sel_hi:[1,0]
	v_pk_mul_f32 v[2:3], v[2:3], v[14:15] op_sel_hi:[1,0]
	v_pk_mul_f32 v[16:17], v[16:17], v[14:15] op_sel_hi:[1,0]
	v_pk_mul_f32 v[18:19], v[18:19], v[14:15] op_sel_hi:[1,0]
	v_pk_mul_f32 v[12:13], v[12:13], v[14:15] op_sel_hi:[1,0]
	v_pk_mul_f32 v[6:7], v[6:7], v[14:15] op_sel_hi:[1,0]
	v_mul_f32_e32 v20, 0xbfb8aa3b, v5
	v_mul_f32_e32 v21, 0xbfb8aa3b, v1
	v_mul_f32_e32 v22, 0xbfb8aa3b, v9
	v_mul_f32_e32 v25, 0xbfb8aa3b, v3
	v_mul_f32_e32 v14, 0xbfb8aa3b, v17
	v_mul_f32_e32 v15, 0xbfb8aa3b, v19
	v_mul_f32_e32 v23, 0xbfb8aa3b, v13
	v_mul_f32_e32 v24, 0xbfb8aa3b, v7
	v_exp_f32_e32 v20, v20
	v_exp_f32_e32 v21, v21
	v_exp_f32_e32 v22, v22
	v_exp_f32_e32 v25, v25
	v_exp_f32_e32 v14, v14
	v_exp_f32_e32 v15, v15
	v_exp_f32_e32 v23, v23
	v_exp_f32_e32 v24, v24
	v_add_f32_e32 v20, 1.0, v20
	v_add_f32_e32 v21, 1.0, v21
	v_add_f32_e32 v22, 1.0, v22
	v_add_f32_e32 v25, 1.0, v25
	v_add_f32_e32 v14, 1.0, v14
	v_add_f32_e32 v15, 1.0, v15
	v_add_f32_e32 v23, 1.0, v23
	v_add_f32_e32 v24, 1.0, v24
	v_rcp_f32_e32 v20, v20
	v_rcp_f32_e32 v21, v21
	v_rcp_f32_e32 v22, v22
	v_rcp_f32_e32 v25, v25
	v_rcp_f32_e32 v14, v14
	v_rcp_f32_e32 v15, v15
	v_rcp_f32_e32 v23, v23
	v_rcp_f32_e32 v24, v24
	v_mul_f32_e32 v5, v5, v20
	v_mul_f32_e32 v1, v1, v21
	v_mul_f32_e32 v9, v9, v22
	v_mul_f32_e32 v3, v3, v25
	s_andn2_b64 vcc, exec, s[6:7]
	v_mul_f32_e32 v14, v17, v14
	v_mul_f32_e32 v15, v19, v15
	v_mul_f32_e32 v13, v13, v23
	v_mul_f32_e32 v7, v7, v24
	v_mul_f32_e32 v4, v4, v5
	v_mul_f32_e32 v5, v0, v1
	v_mul_f32_e32 v1, v8, v9
	v_mul_f32_e32 v3, v2, v3
	v_mul_f32_e32 v14, v16, v14
	v_mul_f32_e32 v15, v18, v15
	v_mul_f32_e32 v8, v12, v13
	v_mul_f32_e32 v6, v6, v7
	v_cvt_pk_bf16_f32 v0, v14, v4
	v_cvt_pk_bf16_f32 v1, v1, v6
	v_cvt_pk_bf16_f32 v2, v15, v5
	v_cvt_pk_bf16_f32 v3, v8, v3
	global_store_dwordx4 v[10:11], v[0:3], off
	s_cbranch_vccnz .LBB0_925
	s_andn2_b64 vcc, exec, s[0:1]
	s_cbranch_vccnz .LBB0_924
	s_barrier
	s_branch .LBB0_924
